# P7: Horner carry-in loop software-pipelined (2 register sets), per-unit C/D/gain + tile0 loads hoisted to unit start; P1 f32 stores plain
# speedup vs baseline: 1.0013x; 1.0013x over previous
; #define LAS __attribute__((address_space(3)))
; template <int PASS> __device__ __forceinline__ void ssm_unit(int unit, int lane, LAS unsigned char* wl, const bf16* X2, const float* slots, float* RSTD, const float* gmix, const float* AB, const float* A128, const bf16* BB, const bf16* CC, ...
;     ...
;     { const f32x2 abA = *(const f32x2*)(AB + (size_t)(g * 64 + n) * 2), abB = *(const f32x2*)(AB + (size_t)(g * 64 + n + 32) * 2);
;       aA = {abA.x, abA.y}; aB = {abB.x, abB.y};
;       cpx t = cmul(aA, aA); t = cmul(t, t); aA8 = cmul(t, t); t = cmul(aB, aB); t = cmul(t, t); aB8 = cmul(t, t); }
;     bf16x8 bbf[4];
; #pragma unroll
;     for (int b = 0; b < 4; ++b) bbf[b] = ld8_bf16(BB + ((size_t)g * 128 + b * 32 + n) * 16 + 8 * hi);
;     cpx SA = {0.f, 0.f}, SB = {0.f, 0.f};
;     if (PASS == 2) {
;         if (smp) { const size_t o = (size_t)(sc - 128) * 4096 + g * 64 + n; SA = {h0r[o], h0i[o]}; SB = {h0r[o + 32], h0i[o + 32]}; }
;         else {
;             const f32x2 pA = *(const f32x2*)(A128 + (size_t)(g * 64 + n) * 2), pB = *(const f32x2*)(A128 + (size_t)(g * 64 + n + 32) * 2);
;             const cpx qA = {pA.x, pA.y}, qB = {pB.x, pB.y};
;             const int c0 = sc & ~63, nc = sc & 63;
;             const float* ep = E + ((size_t)c0 * 4096 + g * 64 + n) * 2;
; #pragma unroll 4
;             for (int c = 0; c < nc; ++c) { const f32x2 eA = *(const f32x2*)(ep + (size_t)c * 8192), eB = *(const f32x2*)(ep + (size_t)c * 8192 + 64);
;                 SA = cfma(qA, SA, (cpx){eA.x, eA.y}); SB = cfma(qB, SB, (cpx){eB.x, eB.y}); }
;         }
;     }
;     LAS unsigned char* Sl = wl;
;     LAS float* Ul = (LAS float*)(wl + 128 * SSM_IROW);
;     bf16x8 ccf[4]; f32x4 dv = {0.f, 0.f, 0.f, 0.f};
;     const int c16 = lane & 15, kq = lane >> 4;
;     if (PASS == 2) {
; #pragma unroll
;         for (int ks = 0; ks < 4; ++ks) ccf[ks] = ld8_bf16(CC + ((size_t)g * 16 + c16) * 128 + 32 * ks + 8 * kq);
;         dv = *(const f32x4*)(dsk + g * 16 + 4 * kq);
;     }
;     const f32x4 gm0 = *(const f32x4*)(gmix + g * 16 + 8 * hi), gm1 = *(const f32x4*)(gmix + g * 16 + 8 * hi + 4);
;     u32x4 nxw; f32x4 ns0, ns1, ns2, ns3; float nrs = 0.f;
;     ...
;     SSM_LOAD(0);
; __global__ void __launch_bounds__(512, 2) mk_fwd(Params p) {
;     ...
;         for (int u0 = gw; u0 < 144 * 64; u0 += NGW) {
;             int u = u0;
.LBB0_720:
	s_and_b32 s4, s74, 0x7c0
	s_and_b32 s5, s74, 0x800
	s_xor_b32 s14, s4, 0xfc0
	s_cmp_eq_u32 s5, 0
	s_cselect_b32 s4, s4, s14
	s_and_b32 s5, s74, 0xfffff03f
	s_or_b32 s4, s4, s5
	s_cmpk_lt_i32 s74, 0x2000
	s_cselect_b32 s72, s4, s74
	s_and_b32 s4, s72, 63
	s_ashr_i32 s75, s72, 6
	s_cmpk_gt_i32 s75, 0x7f
	s_cselect_b64 s[46:47], -1, 0
	s_cmpk_lt_i32 s75, 0x80
	s_cselect_b64 s[44:45], -1, 0
	s_lshl_b32 s34, s4, 6
	v_or_b32_e32 v1, s34, v162
	v_lshlrev_b32_e32 v0, 1, v1
	v_lshlrev_b32_e32 v2, 3, v1
	v_or_b32_e32 v1, 64, v0
	s_lshl_b32 s5, s4, 11
	v_lshlrev_b32_e32 v1, 2, v1
	global_load_dwordx2 v[128:129], v2, s[64:65]
	global_load_dwordx2 v[130:131], v1, s[64:65]
	v_or_b32_e32 v2, s5, v153
	v_lshlrev_b32_e32 v112, 1, v2
	v_lshl_add_u64 v[2:3], v[114:115], 0, v[112:113]
	global_load_dwordx4 v[64:67], v[2:3], off
	global_load_dwordx4 v[68:71], v[2:3], off offset:1024
	global_load_dwordx4 v[72:75], v[2:3], off offset:2048
	global_load_dwordx4 v[76:79], v[2:3], off offset:3072
	s_and_b32 s98, s72, 0xffffffc0
	s_addk_i32 s98, 0x2000
	s_lshl_b32 s99, s75, 7
	s_and_b64 s[100:101], s[46:47], exec
	s_cselect_b32 s98, s98, s99
	v_or_b32_e32 v207, s5, v159
	v_lshlrev_b32_e32 v208, 1, v207
	v_mov_b32_e32 v209, 0
	v_lshl_add_u64 v[210:211], v[116:117], 0, v[208:209]
	global_load_dwordx4 v[80:83], v[210:211], off
	global_load_dwordx4 v[84:87], v[210:211], off offset:64
	global_load_dwordx4 v[88:91], v[210:211], off offset:128
	global_load_dwordx4 v[92:95], v[210:211], off offset:192
	v_lshl_add_u64 v[210:211], v[118:119], 0, s[34:35]
	global_load_dwordx4 v[96:99], v[210:211], off
	v_lshl_add_u64 v[210:211], v[120:121], 0, s[34:35]
	global_load_dwordx4 v[100:103], v[210:211], off offset:16
	global_load_dwordx4 v[104:107], v[210:211], off
	v_or_b32_e32 v214, s98, v157
	v_ashrrev_i32_e32 v215, 31, v214
	v_lshlrev_b64 v[216:217], 11, v[214:215]
	v_lshl_add_u64 v[216:217], s[20:21], 0, v[216:217]
	s_lshl_b32 s100, s4, 5
	s_mov_b32 s101, s35
	v_lshl_add_u64 v[216:217], v[216:217], 0, s[100:101]
	v_mov_b32_e32 v218, v126
	v_mov_b32_e32 v219, 0
	v_lshl_add_u64 v[216:217], v[216:217], 0, v[218:219]
	v_lshl_add_u64 v[220:221], v[214:215], 2, s[22:23]
	global_load_dwordx4 v[202:205], v[216:217], off
	s_nop 0
	global_load_dword v206, v[220:221], off
	s_mov_b64 s[68:69], -1
	s_and_b64 vcc, exec, s[44:45]
	s_cbranch_vccz .LBB0_731
	s_bfe_u32 s70, s72, 0x60006
	s_cmp_eq_u32 s70, 0
	s_cbranch_scc1 .LBB0_726
	v_lshlrev_b32_e32 v0, 2, v0
	global_load_dwordx2 v[4:5], v1, s[66:67]
	global_load_dwordx2 v[8:9], v0, s[66:67]
	s_and_b32 s68, s75, 0xffffffc0
	s_ashr_i32 s69, s68, 31
	s_lshl_b64 s[68:69], s[68:69], 12
	s_cmp_lt_u32 s70, 4
	s_waitcnt vmcnt(1)
	v_xor_b32_e32 v0, 0x80000000, v5
	v_mov_b32_e32 v2, v4
	v_mov_b32_e32 v3, v4
	v_mov_b32_e32 v1, v5
	s_waitcnt vmcnt(0)
	v_xor_b32_e32 v4, 0x80000000, v9
	v_mov_b32_e32 v6, v8
	v_mov_b32_e32 v7, v8
	v_mov_b32_e32 v5, v9
	s_cbranch_scc1 .LBB0_727
	s_and_b32 s70, s75, 60
	s_add_u32 s76, s34, s68
	s_addc_u32 s77, 0, s69
	v_lshl_add_u64 v[8:9], s[76:77], 0, v[162:163]
	v_mov_b32_e32 v132, 0
	v_lshl_add_u64 v[8:9], v[8:9], 3, s[36:37]
	s_mov_b32 s71, 0
	v_mov_b32_e32 v133, v132
	v_mov_b32_e32 v164, v132
	v_mov_b32_e32 v165, v132
.LBB0_724:
	v_add_co_u32_e32 v10, vcc, 0xfffe8000, v8
	s_nop 0
	s_nop 0
	v_addc_co_u32_e32 v11, vcc, -1, v9, vcc
	v_add_co_u32_e32 v12, vcc, 0xffff0000, v8
	global_load_dwordx2 v[14:15], v[10:11], off offset:-256
	s_nop 0
	global_load_dwordx2 v[10:11], v[10:11], off
	v_addc_co_u32_e32 v13, vcc, -1, v9, vcc
	global_load_dwordx2 v[18:19], v[12:13], off offset:-256
	s_nop 0
	global_load_dwordx2 v[12:13], v[12:13], off
	v_add_co_u32_e32 v16, vcc, 0xffff8000, v8
	s_nop 0
	s_nop 0
	v_addc_co_u32_e32 v17, vcc, -1, v9, vcc
	global_load_dwordx2 v[20:21], v[16:17], off offset:-256
	s_nop 0
	global_load_dwordx2 v[16:17], v[16:17], off
	s_nop 0
	global_load_dwordx2 v[22:23], v[8:9], off offset:-256
	global_load_dwordx2 v[24:25], v[8:9], off
	v_lshl_add_u64 v[8:9], v[8:9], 0, s[38:39]
.Lp7h_A:
	s_add_i32 s71, s71, 4
	s_cmp_lg_u32 s70, s71
	s_cbranch_scc0 .Lp7h_lastA
	v_add_co_u32_e32 v186, vcc, 0xfffe8000, v8
	s_nop 0
	s_nop 0
	v_addc_co_u32_e32 v187, vcc, -1, v9, vcc
	v_add_co_u32_e32 v188, vcc, 0xffff0000, v8
	global_load_dwordx2 v[190:191], v[186:187], off offset:-256
	s_nop 0
	global_load_dwordx2 v[186:187], v[186:187], off
	v_addc_co_u32_e32 v189, vcc, -1, v9, vcc
	global_load_dwordx2 v[194:195], v[188:189], off offset:-256
	s_nop 0
	global_load_dwordx2 v[188:189], v[188:189], off
	v_add_co_u32_e32 v192, vcc, 0xffff8000, v8
	s_nop 0
	s_nop 0
	v_addc_co_u32_e32 v193, vcc, -1, v9, vcc
	global_load_dwordx2 v[196:197], v[192:193], off offset:-256
	s_nop 0
	global_load_dwordx2 v[192:193], v[192:193], off
	s_nop 0
	global_load_dwordx2 v[198:199], v[8:9], off offset:-256
	global_load_dwordx2 v[200:201], v[8:9], off
	v_lshl_add_u64 v[8:9], v[8:9], 0, s[38:39]
	s_waitcnt vmcnt(15)
	v_pk_fma_f32 v[14:15], v[4:5], v[164:165], v[14:15]
	s_waitcnt vmcnt(14)
	v_pk_fma_f32 v[10:11], v[0:1], v[132:133], v[10:11]
	v_pk_fma_f32 v[14:15], v[6:7], v[164:165], v[14:15] op_sel:[0,0,1] op_sel_hi:[1,1,0]
	v_pk_fma_f32 v[10:11], v[2:3], v[132:133], v[10:11] op_sel:[0,0,1] op_sel_hi:[1,1,0]
	s_waitcnt vmcnt(13)
	v_pk_fma_f32 v[18:19], v[4:5], v[14:15], v[18:19]
	s_waitcnt vmcnt(12)
	v_pk_fma_f32 v[12:13], v[0:1], v[10:11], v[12:13]
	v_pk_fma_f32 v[14:15], v[6:7], v[14:15], v[18:19] op_sel:[0,0,1] op_sel_hi:[1,1,0]
	v_pk_fma_f32 v[10:11], v[2:3], v[10:11], v[12:13] op_sel:[0,0,1] op_sel_hi:[1,1,0]
	s_waitcnt vmcnt(11)
	v_pk_fma_f32 v[12:13], v[4:5], v[14:15], v[20:21]
	s_waitcnt vmcnt(10)
	v_pk_fma_f32 v[16:17], v[0:1], v[10:11], v[16:17]
	v_pk_fma_f32 v[12:13], v[6:7], v[14:15], v[12:13] op_sel:[0,0,1] op_sel_hi:[1,1,0]
	v_pk_fma_f32 v[10:11], v[2:3], v[10:11], v[16:17] op_sel:[0,0,1] op_sel_hi:[1,1,0]
	s_waitcnt vmcnt(9)
	v_pk_fma_f32 v[14:15], v[4:5], v[12:13], v[22:23]
	s_waitcnt vmcnt(8)
	v_pk_fma_f32 v[16:17], v[0:1], v[10:11], v[24:25]
	v_pk_fma_f32 v[164:165], v[6:7], v[12:13], v[14:15] op_sel:[0,0,1] op_sel_hi:[1,1,0]
	v_pk_fma_f32 v[132:133], v[2:3], v[10:11], v[16:17] op_sel:[0,0,1] op_sel_hi:[1,1,0]
	s_add_i32 s71, s71, 4
	s_cmp_lg_u32 s70, s71
	s_cbranch_scc0 .Lp7h_lastB
; __device__ __forceinline__ cpx cfma(cpx a, cpx b, cpx c) { return {fmaf(a.r, b.r, fmaf(-a.i, b.i, c.r)), fmaf(a.r, b.i, fmaf(a.i, b.r, c.i))}; }
; template <int PASS> __device__ __forceinline__ void ssm_unit(int unit, int lane, LAS unsigned char* wl, const bf16* X2, const float* slots, float* RSTD, const float* gmix, const float* AB, const float* A128, const bf16* BB, const bf16* CC, ...
;     ...
;             const int c0 = sc & ~63, nc = sc & 63;
;             const float* ep = E + ((size_t)c0 * 4096 + g * 64 + n) * 2;
; #pragma unroll 4
;             for (int c = 0; c < nc; ++c) { const f32x2 eA = *(const f32x2*)(ep + (size_t)c * 8192), eB = *(const f32x2*)(ep + (size_t)c * 8192 + 64);
;                 SA = cfma(qA, SA, (cpx){eA.x, eA.y}); SB = cfma(qB, SB, (cpx){eB.x, eB.y}); }
	v_add_co_u32_e32 v10, vcc, 0xfffe8000, v8
	s_nop 0
	s_nop 0
	v_addc_co_u32_e32 v11, vcc, -1, v9, vcc
	v_add_co_u32_e32 v12, vcc, 0xffff0000, v8
	global_load_dwordx2 v[14:15], v[10:11], off offset:-256
	s_nop 0
	global_load_dwordx2 v[10:11], v[10:11], off
	v_addc_co_u32_e32 v13, vcc, -1, v9, vcc
	global_load_dwordx2 v[18:19], v[12:13], off offset:-256
	s_nop 0
	global_load_dwordx2 v[12:13], v[12:13], off
	v_add_co_u32_e32 v16, vcc, 0xffff8000, v8
	s_nop 0
	s_nop 0
	v_addc_co_u32_e32 v17, vcc, -1, v9, vcc
	global_load_dwordx2 v[20:21], v[16:17], off offset:-256
	s_nop 0
	global_load_dwordx2 v[16:17], v[16:17], off
	s_nop 0
	global_load_dwordx2 v[22:23], v[8:9], off offset:-256
	global_load_dwordx2 v[24:25], v[8:9], off
	v_lshl_add_u64 v[8:9], v[8:9], 0, s[38:39]
	s_waitcnt vmcnt(15)
	v_pk_fma_f32 v[190:191], v[4:5], v[164:165], v[190:191]
	s_waitcnt vmcnt(14)
	v_pk_fma_f32 v[186:187], v[0:1], v[132:133], v[186:187]
	v_pk_fma_f32 v[190:191], v[6:7], v[164:165], v[190:191] op_sel:[0,0,1] op_sel_hi:[1,1,0]
	v_pk_fma_f32 v[186:187], v[2:3], v[132:133], v[186:187] op_sel:[0,0,1] op_sel_hi:[1,1,0]
	s_waitcnt vmcnt(13)
	v_pk_fma_f32 v[194:195], v[4:5], v[190:191], v[194:195]
	s_waitcnt vmcnt(12)
	v_pk_fma_f32 v[188:189], v[0:1], v[186:187], v[188:189]
	v_pk_fma_f32 v[190:191], v[6:7], v[190:191], v[194:195] op_sel:[0,0,1] op_sel_hi:[1,1,0]
	v_pk_fma_f32 v[186:187], v[2:3], v[186:187], v[188:189] op_sel:[0,0,1] op_sel_hi:[1,1,0]
	s_waitcnt vmcnt(11)
	v_pk_fma_f32 v[188:189], v[4:5], v[190:191], v[196:197]
	s_waitcnt vmcnt(10)
	v_pk_fma_f32 v[192:193], v[0:1], v[186:187], v[192:193]
	v_pk_fma_f32 v[188:189], v[6:7], v[190:191], v[188:189] op_sel:[0,0,1] op_sel_hi:[1,1,0]
	v_pk_fma_f32 v[186:187], v[2:3], v[186:187], v[192:193] op_sel:[0,0,1] op_sel_hi:[1,1,0]
	s_waitcnt vmcnt(9)
	v_pk_fma_f32 v[190:191], v[4:5], v[188:189], v[198:199]
	s_waitcnt vmcnt(8)
	v_pk_fma_f32 v[192:193], v[0:1], v[186:187], v[200:201]
	v_pk_fma_f32 v[164:165], v[6:7], v[188:189], v[190:191] op_sel:[0,0,1] op_sel_hi:[1,1,0]
	v_pk_fma_f32 v[132:133], v[2:3], v[186:187], v[192:193] op_sel:[0,0,1] op_sel_hi:[1,1,0]
	s_branch .Lp7h_A
.Lp7h_lastA:
	s_waitcnt vmcnt(7)
	v_pk_fma_f32 v[14:15], v[4:5], v[164:165], v[14:15]
	s_waitcnt vmcnt(6)
	v_pk_fma_f32 v[10:11], v[0:1], v[132:133], v[10:11]
	v_pk_fma_f32 v[14:15], v[6:7], v[164:165], v[14:15] op_sel:[0,0,1] op_sel_hi:[1,1,0]
	v_pk_fma_f32 v[10:11], v[2:3], v[132:133], v[10:11] op_sel:[0,0,1] op_sel_hi:[1,1,0]
	s_waitcnt vmcnt(5)
	v_pk_fma_f32 v[18:19], v[4:5], v[14:15], v[18:19]
	s_waitcnt vmcnt(4)
	v_pk_fma_f32 v[12:13], v[0:1], v[10:11], v[12:13]
	v_pk_fma_f32 v[14:15], v[6:7], v[14:15], v[18:19] op_sel:[0,0,1] op_sel_hi:[1,1,0]
	v_pk_fma_f32 v[10:11], v[2:3], v[10:11], v[12:13] op_sel:[0,0,1] op_sel_hi:[1,1,0]
	s_waitcnt vmcnt(3)
	v_pk_fma_f32 v[12:13], v[4:5], v[14:15], v[20:21]
	s_waitcnt vmcnt(2)
	v_pk_fma_f32 v[16:17], v[0:1], v[10:11], v[16:17]
	v_pk_fma_f32 v[12:13], v[6:7], v[14:15], v[12:13] op_sel:[0,0,1] op_sel_hi:[1,1,0]
	v_pk_fma_f32 v[10:11], v[2:3], v[10:11], v[16:17] op_sel:[0,0,1] op_sel_hi:[1,1,0]
	s_waitcnt vmcnt(1)
	v_pk_fma_f32 v[14:15], v[4:5], v[12:13], v[22:23]
	s_waitcnt vmcnt(0)
	v_pk_fma_f32 v[16:17], v[0:1], v[10:11], v[24:25]
	v_pk_fma_f32 v[164:165], v[6:7], v[12:13], v[14:15] op_sel:[0,0,1] op_sel_hi:[1,1,0]
	v_pk_fma_f32 v[132:133], v[2:3], v[10:11], v[16:17] op_sel:[0,0,1] op_sel_hi:[1,1,0]
	s_branch .Lp7h_done
.Lp7h_lastB:
	s_waitcnt vmcnt(7)
	v_pk_fma_f32 v[190:191], v[4:5], v[164:165], v[190:191]
	s_waitcnt vmcnt(6)
	v_pk_fma_f32 v[186:187], v[0:1], v[132:133], v[186:187]
	v_pk_fma_f32 v[190:191], v[6:7], v[164:165], v[190:191] op_sel:[0,0,1] op_sel_hi:[1,1,0]
	v_pk_fma_f32 v[186:187], v[2:3], v[132:133], v[186:187] op_sel:[0,0,1] op_sel_hi:[1,1,0]
	s_waitcnt vmcnt(5)
	v_pk_fma_f32 v[194:195], v[4:5], v[190:191], v[194:195]
	s_waitcnt vmcnt(4)
	v_pk_fma_f32 v[188:189], v[0:1], v[186:187], v[188:189]
	v_pk_fma_f32 v[190:191], v[6:7], v[190:191], v[194:195] op_sel:[0,0,1] op_sel_hi:[1,1,0]
	v_pk_fma_f32 v[186:187], v[2:3], v[186:187], v[188:189] op_sel:[0,0,1] op_sel_hi:[1,1,0]
	s_waitcnt vmcnt(3)
	v_pk_fma_f32 v[188:189], v[4:5], v[190:191], v[196:197]
	s_waitcnt vmcnt(2)
	v_pk_fma_f32 v[192:193], v[0:1], v[186:187], v[192:193]
	v_pk_fma_f32 v[188:189], v[6:7], v[190:191], v[188:189] op_sel:[0,0,1] op_sel_hi:[1,1,0]
	v_pk_fma_f32 v[186:187], v[2:3], v[186:187], v[192:193] op_sel:[0,0,1] op_sel_hi:[1,1,0]
	s_waitcnt vmcnt(1)
	v_pk_fma_f32 v[190:191], v[4:5], v[188:189], v[198:199]
	s_waitcnt vmcnt(0)
	v_pk_fma_f32 v[192:193], v[0:1], v[186:187], v[200:201]
	v_pk_fma_f32 v[164:165], v[6:7], v[188:189], v[190:191] op_sel:[0,0,1] op_sel_hi:[1,1,0]
	v_pk_fma_f32 v[132:133], v[2:3], v[186:187], v[192:193] op_sel:[0,0,1] op_sel_hi:[1,1,0]
.Lp7h_done:
	s_bfe_u32 s71, s72, 0x20006
	s_cmp_eq_u32 s71, 0
	s_cbranch_scc0 .LBB0_728
	s_branch .LBB0_730

; #define LAS __attribute__((address_space(3)))
; template <bool FULL> __device__ __forceinline__ void scan32p(f32x16& xr, f32x16& xi, const cpx a1, const cpx a8, cpx& S, int hi) {
;     f32x2 Lr[8], Li[8];
;     Lr[0] = (f32x2){xr[0], xr[1]}; Li[0] = (f32x2){xi[0], xi[1]};
;     const float ar = a1.r, ai = a1.i;
; #pragma unroll
;     for (int q = 1; q < 8; ++q) {
;         const f32x2 vr = {xr[2 * q], xr[2 * q + 1]}, vi = {xi[2 * q], xi[2 * q + 1]};
;         Lr[q] = ar * Lr[q - 1] - ai * Li[q - 1] + vr; Li[q] = ar * Li[q - 1] + ai * Lr[q - 1] + vi;
;     }
;     const cpx mP = {Lr[7].x, Li[7].x}, mQ = {Lr[7].y, Li[7].y};
;     const cpx oP = {__shfl_xor(mP.r, 32), __shfl_xor(mP.i, 32)}, oQ = {__shfl_xor(mQ.r, 32), __shfl_xor(mQ.i, 32)};
;     const cpx e0P = hi == 0 ? mP : oP, e0Q = hi == 0 ? mQ : oQ, e1P = hi == 0 ? oP : mP, e1Q = hi == 0 ? oQ : mQ;
;     cpx c = S; const cpx cP0 = c; c = cfma(a8, c, e0P); const cpx cQ0 = c; c = cfma(a8, c, e0Q); const cpx cP1 = c; c = cfma(a8, c, e1P); const cpx cQ1 = c; c = cfma(a8, c, e1Q);
;     S = c;
; template <int PASS> __device__ __forceinline__ void ssm_unit(int unit, int lane, LAS unsigned char* wl, const bf16* X2, const float* slots, float* RSTD, const float* gmix, const float* AB, const float* A128, const bf16* BB, const bf16* CC, ...
;     ...
;     for (int t = 0; t < ntile; ++t) {
;         f32x4 u0 = bf4lo(nxw), u1 = bf4hi(nxw); float rs = nrs;
;         if (PASS == 1) {
;             const f32x4 sv = (ns0 + ns1) + (ns2 + ns3); rs = __builtin_amdgcn_rsqf(((sv[0] + sv[1]) + (sv[2] + sv[3])) * (1.0f / D) + EPS);
;             if (g == 0 && hi == 0) RSTD[row0 + t * 32 + tok] = rs;
;         }
;         if (t + 1 < ntile) SSM_LOAD(t + 1);
;         u0 = u0 * rs * gm0; u1 = u1 * rs * gm1;
;         u32x4 uw; uw.x = pk2(u0[0], u0[1]); uw.y = pk2(u0[2], u0[3]); uw.z = pk2(u1[0], u1[1]); uw.w = pk2(u1[2], u1[3]);
;         const bf16x8 uf = __builtin_bit_cast(bf16x8, uw);
;         if (PASS == 2) { *(LAS f32x4*)(Ul + tok * 16 + 8 * hi) = u0; *(LAS f32x4*)(Ul + tok * 16 + 8 * hi + 4) = u1; }
;         f32x16 X[4];
; #pragma unroll
;         for (int b = 0; b < 4; ++b) {
; #pragma unroll
;             for (int i = 0; i < 16; ++i) X[b][i] = 0.f;
;             X[b] = MFMA32(uf, bbf[b], X[b]);
;         }
;         scan32p<PASS == 2>(X[0], X[2], aA, aA8, SA, hi);
.LBB0_733:
	s_and_b32 s14, s72, 0xffffffc0
	s_addk_i32 s14, 0x2000
	s_and_b64 s[68:69], s[46:47], exec
	s_cselect_b32 s68, 2, 4
	s_lshl_b32 s15, s75, 7
	s_and_b64 s[46:47], s[46:47], exec
	s_cselect_b32 s14, s14, s15
	s_lshl_b32 s4, s4, 5
	s_mov_b32 s5, s35
	v_mov_b32_e32 v127, v113
	s_waitcnt vmcnt(14)
	v_pk_mul_f32 v[8:9], v[128:129], v[128:129] op_sel:[0,1] op_sel_hi:[1,0]
	s_waitcnt vmcnt(13)
	v_pk_mul_f32 v[14:15], v[130:131], v[130:131] op_sel:[0,1] op_sel_hi:[1,0]
	v_mul_f32_e32 v6, v129, v129
	v_pk_add_f32 v[8:9], v[8:9], v[8:9]
	v_mul_f32_e32 v12, v131, v131
	v_pk_add_f32 v[14:15], v[14:15], v[14:15]
	v_pk_fma_f32 v[6:7], v[128:129], v[128:129], v[6:7] op_sel_hi:[1,1,0] neg_lo:[0,0,1] neg_hi:[0,0,1]
	v_pk_mul_f32 v[10:11], v[8:9], v[8:9]
	v_pk_fma_f32 v[12:13], v[130:131], v[130:131], v[12:13] op_sel_hi:[1,1,0] neg_lo:[0,0,1] neg_hi:[0,0,1]
	v_pk_mul_f32 v[16:17], v[14:15], v[14:15]
	v_pk_fma_f32 v[10:11], v[6:7], v[6:7], v[10:11] neg_lo:[0,0,1] neg_hi:[0,0,1]
	v_pk_mul_f32 v[6:7], v[6:7], v[8:9]
	v_pk_fma_f32 v[16:17], v[12:13], v[12:13], v[16:17] neg_lo:[0,0,1] neg_hi:[0,0,1]
	v_pk_mul_f32 v[12:13], v[12:13], v[14:15]
	v_pk_add_f32 v[6:7], v[6:7], v[6:7]
	v_pk_add_f32 v[12:13], v[12:13], v[12:13]
	v_mul_f32_e32 v5, v16, v16
	v_pk_mul_f32 v[8:9], v[10:11], v[6:7]
	v_pk_mul_f32 v[14:15], v[16:17], v[12:13]
	v_fma_f32 v146, -v12, v12, v5
	v_mul_f32_e32 v5, v10, v10
	v_pk_add_f32 v[134:135], v[8:9], v[8:9]
	v_pk_add_f32 v[136:137], v[14:15], v[14:15]
	v_fma_f32 v148, -v6, v6, v5
	v_lshl_add_u64 v[138:139], v[122:123], 0, s[4:5]
	v_mov_b32_e32 v140, v128
	v_mov_b32_e32 v141, v128
	v_mov_b32_e32 v128, v129
	v_xor_b32_e32 v135, 0x80000000, v134
	v_mov_b32_e32 v142, v130
	v_mov_b32_e32 v143, v130
	v_mov_b32_e32 v130, v131
	v_xor_b32_e32 v137, 0x80000000, v136
	v_lshl_add_u64 v[144:145], v[124:125], 0, s[4:5]
	v_mov_b32_e32 v147, v146
	v_mov_b32_e32 v149, v148
	v_or_b32_e32 v150, s14, v152
	v_add_u32_e32 v154, s14, v168
	s_mov_b32 s46, 0
	s_waitcnt vmcnt(1)
	v_mov_b64_e32 v[0:1], v[202:203]
	v_mov_b64_e32 v[2:3], v[204:205]
	v_mov_b64_e32 v[110:111], v[204:205]
	v_mov_b64_e32 v[108:109], v[202:203]
	s_branch .LBB0_735
.LBB0_734:
	v_lshlrev_b32_e32 v6, 16, v0
	v_and_b32_e32 v7, 0xffff0000, v0
	v_lshlrev_b32_e32 v0, 16, v1
	v_and_b32_e32 v1, 0xffff0000, v1
	v_lshlrev_b32_e32 v8, 16, v2
	v_and_b32_e32 v9, 0xffff0000, v2
	v_lshlrev_b32_e32 v2, 16, v3
	v_and_b32_e32 v3, 0xffff0000, v3
	v_pk_mul_f32 v[0:1], v[4:5], v[0:1] op_sel_hi:[0,1]
	v_pk_mul_f32 v[6:7], v[4:5], v[6:7] op_sel_hi:[0,1]
	v_pk_mul_f32 v[18:19], v[106:107], v[0:1]
	v_pk_mul_f32 v[0:1], v[4:5], v[8:9] op_sel_hi:[0,1]
	v_pk_mul_f32 v[2:3], v[4:5], v[2:3] op_sel_hi:[0,1]
	v_pk_mul_f32 v[16:17], v[104:105], v[6:7]
	v_pk_mul_f32 v[22:23], v[102:103], v[2:3]
	v_pk_mul_f32 v[20:21], v[100:101], v[0:1]
	v_cvt_pk_bf16_f32 v24, v16, v17
	v_cvt_pk_bf16_f32 v25, v18, v19
	v_cvt_pk_bf16_f32 v26, v20, v21
	v_cvt_pk_bf16_f32 v27, v22, v23
	ds_write_b128 v166, v[16:19] offset:9216
	ds_write_b128 v166, v[20:23] offset:9232
	v_mfma_f32_32x32x16_bf16 v[48:63], v[24:27], v[72:75], 0
	v_add_u32_e32 v154, 32, v154
	s_cmp_eq_u32 s68, s46
	s_nop 9
	v_pk_mul_f32 v[16:17], v[128:129], v[48:49]
	v_mfma_f32_32x32x16_bf16 v[32:47], v[24:27], v[64:67], 0
	v_mfma_f32_32x32x16_bf16 v[0:15], v[24:27], v[68:71], 0
	s_nop 10
	v_fma_f32 v16, v140, v32, -v16
	v_fma_f32 v17, v141, v33, -v17
	v_add_f32_e64 v174, v34, v16
	v_add_f32_e64 v175, v35, v17
	v_mul_f32_e64 v16, v128, v32
	v_mul_f32_e64 v17, v129, v33
	v_pk_fma_f32 v[16:17], v[140:141], v[48:49], v[16:17]
	s_nop 0
	v_pk_add_f32 v[50:51], v[50:51], v[16:17]
	s_nop 0
	v_pk_mul_f32 v[16:17], v[128:129], v[50:51]
	s_nop 0
	v_pk_fma_f32 v[16:17], v[140:141], v[174:175], v[16:17] neg_lo:[0,0,1] neg_hi:[0,0,1]
	s_nop 0
	v_pk_add_f32 v[176:177], v[36:37], v[16:17]
	v_pk_mul_f32 v[16:17], v[128:129], v[174:175]
	s_nop 0
	v_pk_fma_f32 v[16:17], v[140:141], v[50:51], v[16:17]
	s_nop 0
	v_pk_add_f32 v[52:53], v[52:53], v[16:17]
	s_nop 0
	v_pk_mul_f32 v[16:17], v[128:129], v[52:53]
	s_nop 0
	v_pk_fma_f32 v[16:17], v[140:141], v[176:177], v[16:17] neg_lo:[0,0,1] neg_hi:[0,0,1]
	s_nop 0
	v_pk_add_f32 v[38:39], v[38:39], v[16:17]
	v_pk_mul_f32 v[16:17], v[128:129], v[176:177]
	s_nop 0
	v_pk_fma_f32 v[16:17], v[140:141], v[52:53], v[16:17]
	s_nop 0
	v_pk_add_f32 v[54:55], v[54:55], v[16:17]
	s_nop 0
	v_pk_mul_f32 v[16:17], v[128:129], v[54:55]
	s_nop 0
	v_pk_fma_f32 v[16:17], v[140:141], v[38:39], v[16:17] neg_lo:[0,0,1] neg_hi:[0,0,1]
	s_nop 0
	v_pk_add_f32 v[40:41], v[40:41], v[16:17]
	v_pk_mul_f32 v[16:17], v[128:129], v[38:39]
	s_nop 0
	v_pk_fma_f32 v[16:17], v[140:141], v[54:55], v[16:17]
	s_nop 0
	v_pk_add_f32 v[56:57], v[56:57], v[16:17]
	s_nop 0
	v_pk_mul_f32 v[16:17], v[128:129], v[56:57]
	s_nop 0
	v_pk_fma_f32 v[16:17], v[140:141], v[40:41], v[16:17] neg_lo:[0,0,1] neg_hi:[0,0,1]
	s_nop 0
	v_pk_add_f32 v[42:43], v[42:43], v[16:17]
	v_pk_mul_f32 v[16:17], v[128:129], v[40:41]
	s_nop 0
	v_pk_fma_f32 v[16:17], v[140:141], v[56:57], v[16:17]
	s_nop 0
	v_pk_add_f32 v[58:59], v[58:59], v[16:17]
	s_nop 0
	v_pk_mul_f32 v[16:17], v[128:129], v[58:59]
	s_nop 0
	v_pk_fma_f32 v[16:17], v[140:141], v[42:43], v[16:17] neg_lo:[0,0,1] neg_hi:[0,0,1]
	s_nop 0
	v_pk_add_f32 v[44:45], v[44:45], v[16:17]
	v_pk_mul_f32 v[16:17], v[128:129], v[42:43]
	s_nop 0
	v_pk_fma_f32 v[16:17], v[140:141], v[58:59], v[16:17]
	s_nop 0
	v_pk_add_f32 v[60:61], v[60:61], v[16:17]
	s_nop 0
	v_pk_mul_f32 v[16:17], v[128:129], v[60:61]
	s_nop 0
	v_pk_fma_f32 v[16:17], v[140:141], v[44:45], v[16:17] neg_lo:[0,0,1] neg_hi:[0,0,1]
	s_nop 0
	v_pk_add_f32 v[46:47], v[46:47], v[16:17]
	v_pk_mul_f32 v[16:17], v[128:129], v[44:45]
	ds_bpermute_b32 v36, v167, v46
	v_pk_fma_f32 v[16:17], v[140:141], v[60:61], v[16:17]
	ds_bpermute_b32 v127, v167, v47
	v_pk_add_f32 v[62:63], v[62:63], v[16:17]
	ds_bpermute_b32 v37, v167, v62
	ds_bpermute_b32 v151, v167, v63
	s_waitcnt lgkmcnt(3)
; __device__ __forceinline__ cpx cfma(cpx a, cpx b, cpx c) { return {fmaf(a.r, b.r, fmaf(-a.i, b.i, c.r)), fmaf(a.r, b.i, fmaf(a.i, b.r, c.i))}; }
; template <bool FULL> __device__ __forceinline__ void scan32p(f32x16& xr, f32x16& xi, const cpx a1, const cpx a8, cpx& S, int hi) {
;     f32x2 Lr[8], Li[8];
;     Lr[0] = (f32x2){xr[0], xr[1]}; Li[0] = (f32x2){xi[0], xi[1]};
;     const float ar = a1.r, ai = a1.i;
; #pragma unroll
;     for (int q = 1; q < 8; ++q) {
;         const f32x2 vr = {xr[2 * q], xr[2 * q + 1]}, vi = {xi[2 * q], xi[2 * q + 1]};
;         Lr[q] = ar * Lr[q - 1] - ai * Li[q - 1] + vr; Li[q] = ar * Li[q - 1] + ai * Lr[q - 1] + vi;
;     }
;     const cpx mP = {Lr[7].x, Li[7].x}, mQ = {Lr[7].y, Li[7].y};
;     const cpx oP = {__shfl_xor(mP.r, 32), __shfl_xor(mP.i, 32)}, oQ = {__shfl_xor(mQ.r, 32), __shfl_xor(mQ.i, 32)};
;     const cpx e0P = hi == 0 ? mP : oP, e0Q = hi == 0 ? mQ : oQ, e1P = hi == 0 ? oP : mP, e1Q = hi == 0 ? oQ : mQ;
;     cpx c = S; const cpx cP0 = c; c = cfma(a8, c, e0P); const cpx cQ0 = c; c = cfma(a8, c, e0Q); const cpx cP1 = c; c = cfma(a8, c, e1P); const cpx cQ1 = c; c = cfma(a8, c, e1Q);
;     S = c;
;     if (FULL) {
;         const cpx myP = hi == 0 ? cP0 : cP1, myQ = hi == 0 ? cQ0 : cQ1;
;         f32x2 dr = {myP.r, myQ.r}, di = {myP.i, myQ.i};
; #pragma unroll
;         for (int q = 0; q < 8; ++q) {
;             const f32x2 tr = ar * dr - ai * di, ti = ar * di + ai * dr; dr = tr; di = ti;
;             const f32x2 sr = Lr[q] + dr, si = Li[q] + di;
;             xr[2 * q] = sr.x; xr[2 * q + 1] = sr.y; xi[2 * q] = si.x; xi[2 * q + 1] = si.y;
;         }
;     }
; }
	v_cndmask_b32_e64 v35, v36, v46, s[6:7]
	v_mfma_f32_32x32x16_bf16 v[16:31], v[24:27], v[76:79], 0
	s_waitcnt lgkmcnt(1)
	v_cndmask_b32_e64 v34, v37, v62, s[6:7]
	v_fma_f32 v34, v134, v165, v34
	v_fma_f32 v35, v135, v164, v35
	v_fma_f32 v178, v148, v164, v34
	v_fma_f32 v179, v149, v165, v35
	v_cndmask_b32_e64 v35, v127, v47, s[6:7]
	s_waitcnt lgkmcnt(0)
	v_cndmask_b32_e64 v34, v151, v63, s[6:7]
	v_pk_fma_f32 v[34:35], v[134:135], v[178:179], v[34:35] op_sel:[0,1,0] op_sel_hi:[1,0,1]
	s_nop 0
	v_pk_fma_f32 v[180:181], v[148:149], v[178:179], v[34:35]
	v_cndmask_b32_e64 v35, v46, v36, s[6:7]
	v_cndmask_b32_e64 v34, v62, v37, s[6:7]
	v_pk_fma_f32 v[34:35], v[134:135], v[180:181], v[34:35] op_sel:[0,1,0] op_sel_hi:[1,0,1]
	v_cndmask_b32_e64 v182, v181, v165, s[6:7]
	v_pk_fma_f32 v[34:35], v[148:149], v[180:181], v[34:35]
	v_cndmask_b32_e64 v164, v180, v164, s[6:7]
	v_cndmask_b32_e64 v165, v34, v178, s[6:7]
	v_cndmask_b32_e64 v183, v35, v179, s[6:7]
	v_pk_mul_f32 v[178:179], v[128:129], v[164:165]
	v_pk_mul_f32 v[164:165], v[140:141], v[164:165]
	v_pk_fma_f32 v[178:179], v[140:141], v[182:183], v[178:179] neg_lo:[0,0,1] neg_hi:[0,0,1]
	v_pk_fma_f32 v[164:165], v[128:129], v[182:183], v[164:165]
	v_pk_add_f32 v[32:33], v[32:33], v[178:179]
	v_pk_mul_f32 v[180:181], v[128:129], v[164:165]
	v_pk_add_f32 v[48:49], v[48:49], v[164:165]
	v_pk_fma_f32 v[180:181], v[140:141], v[178:179], v[180:181] neg_lo:[0,0,1] neg_hi:[0,0,1]
	v_pk_mul_f32 v[178:179], v[128:129], v[178:179]
	v_pk_add_f32 v[174:175], v[174:175], v[180:181]
	v_pk_fma_f32 v[164:165], v[140:141], v[164:165], v[178:179]
	v_cndmask_b32_e64 v37, v47, v127, s[6:7]
	v_pk_mul_f32 v[178:179], v[128:129], v[164:165]
	v_pk_add_f32 v[50:51], v[50:51], v[164:165]
	v_pk_fma_f32 v[178:179], v[140:141], v[180:181], v[178:179] neg_lo:[0,0,1] neg_hi:[0,0,1]
	v_pk_mul_f32 v[180:181], v[128:129], v[180:181]
	v_pk_add_f32 v[176:177], v[176:177], v[178:179]
	v_pk_fma_f32 v[164:165], v[140:141], v[164:165], v[180:181]
	v_cndmask_b32_e64 v36, v63, v151, s[6:7]
	v_pk_mul_f32 v[180:181], v[128:129], v[164:165]
	v_pk_add_f32 v[52:53], v[52:53], v[164:165]
	v_pk_fma_f32 v[180:181], v[140:141], v[178:179], v[180:181] neg_lo:[0,0,1] neg_hi:[0,0,1]
	v_pk_mul_f32 v[178:179], v[128:129], v[178:179]
	v_pk_add_f32 v[38:39], v[38:39], v[180:181]
	v_pk_fma_f32 v[164:165], v[140:141], v[164:165], v[178:179]
	v_pk_fma_f32 v[36:37], v[134:135], v[34:35], v[36:37] op_sel:[0,1,0] op_sel_hi:[1,0,1]
	v_pk_mul_f32 v[178:179], v[128:129], v[164:165]
	v_pk_add_f32 v[54:55], v[54:55], v[164:165]
	v_pk_fma_f32 v[178:179], v[140:141], v[180:181], v[178:179] neg_lo:[0,0,1] neg_hi:[0,0,1]
	v_pk_mul_f32 v[180:181], v[128:129], v[180:181]
	v_pk_add_f32 v[40:41], v[40:41], v[178:179]
	v_pk_fma_f32 v[164:165], v[140:141], v[164:165], v[180:181]
	s_nop 0
	v_pk_mul_f32 v[180:181], v[128:129], v[164:165]
	v_pk_add_f32 v[56:57], v[56:57], v[164:165]
	v_pk_fma_f32 v[180:181], v[140:141], v[178:179], v[180:181] neg_lo:[0,0,1] neg_hi:[0,0,1]
	v_pk_mul_f32 v[178:179], v[128:129], v[178:179]
	v_pk_add_f32 v[42:43], v[42:43], v[180:181]
	v_pk_fma_f32 v[164:165], v[140:141], v[164:165], v[178:179]
	s_nop 0
	v_pk_mul_f32 v[178:179], v[128:129], v[164:165]
	v_pk_add_f32 v[58:59], v[58:59], v[164:165]
	v_pk_fma_f32 v[178:179], v[140:141], v[180:181], v[178:179] neg_lo:[0,0,1] neg_hi:[0,0,1]
	v_pk_mul_f32 v[180:181], v[128:129], v[180:181]
	v_pk_add_f32 v[44:45], v[44:45], v[178:179]
	v_pk_fma_f32 v[164:165], v[140:141], v[164:165], v[180:181]
	s_nop 0
	v_pk_mul_f32 v[180:181], v[128:129], v[164:165]
	v_pk_add_f32 v[60:61], v[60:61], v[164:165]
	v_pk_fma_f32 v[180:181], v[140:141], v[178:179], v[180:181] neg_lo:[0,0,1] neg_hi:[0,0,1]
	v_pk_mul_f32 v[178:179], v[128:129], v[178:179]
	v_pk_add_f32 v[46:47], v[46:47], v[180:181]
	v_pk_fma_f32 v[164:165], v[140:141], v[164:165], v[178:179]
	v_pk_mul_f32 v[178:179], v[130:131], v[16:17]
	v_pk_add_f32 v[62:63], v[62:63], v[164:165]
	v_pk_fma_f32 v[178:179], v[142:143], v[0:1], v[178:179] neg_lo:[0,0,1] neg_hi:[0,0,1]
	s_nop 0
	v_pk_add_f32 v[178:179], v[2:3], v[178:179]
	v_pk_mul_f32 v[2:3], v[130:131], v[0:1]
	s_nop 0
	v_pk_fma_f32 v[2:3], v[142:143], v[16:17], v[2:3]
	s_nop 0
	v_pk_add_f32 v[18:19], v[18:19], v[2:3]
	s_nop 0
	v_pk_mul_f32 v[2:3], v[130:131], v[18:19]
	s_nop 0
	v_pk_fma_f32 v[2:3], v[142:143], v[178:179], v[2:3] neg_lo:[0,0,1] neg_hi:[0,0,1]
	s_nop 0
	v_pk_add_f32 v[4:5], v[4:5], v[2:3]
	v_pk_mul_f32 v[2:3], v[130:131], v[178:179]
	s_nop 0
	v_pk_fma_f32 v[2:3], v[142:143], v[18:19], v[2:3]
	s_nop 0
	v_pk_add_f32 v[20:21], v[20:21], v[2:3]
	s_nop 0
	v_pk_mul_f32 v[2:3], v[130:131], v[20:21]
	s_nop 0
	v_pk_fma_f32 v[2:3], v[142:143], v[4:5], v[2:3] neg_lo:[0,0,1] neg_hi:[0,0,1]
	s_nop 0
	v_pk_add_f32 v[6:7], v[6:7], v[2:3]
	v_pk_mul_f32 v[2:3], v[130:131], v[4:5]
	s_nop 0
	v_pk_fma_f32 v[2:3], v[142:143], v[20:21], v[2:3]
	s_nop 0
	v_pk_add_f32 v[22:23], v[22:23], v[2:3]
	s_nop 0
	v_pk_mul_f32 v[2:3], v[130:131], v[22:23]
	s_nop 0
	v_pk_fma_f32 v[2:3], v[142:143], v[6:7], v[2:3] neg_lo:[0,0,1] neg_hi:[0,0,1]
	s_nop 0
	v_pk_add_f32 v[8:9], v[8:9], v[2:3]
	v_pk_mul_f32 v[2:3], v[130:131], v[6:7]
	s_nop 0
	v_pk_fma_f32 v[2:3], v[142:143], v[22:23], v[2:3]
	s_nop 0
	v_pk_add_f32 v[24:25], v[24:25], v[2:3]
	s_nop 0
	v_pk_mul_f32 v[2:3], v[130:131], v[24:25]
	s_nop 0
	v_pk_fma_f32 v[2:3], v[142:143], v[8:9], v[2:3] neg_lo:[0,0,1] neg_hi:[0,0,1]
	s_nop 0
	v_pk_add_f32 v[10:11], v[10:11], v[2:3]
	v_pk_mul_f32 v[2:3], v[130:131], v[8:9]
	s_nop 0
	v_pk_fma_f32 v[2:3], v[142:143], v[24:25], v[2:3]
	s_nop 0
	v_pk_add_f32 v[26:27], v[26:27], v[2:3]
	s_nop 0
	v_pk_mul_f32 v[2:3], v[130:131], v[26:27]
	s_nop 0
	v_pk_fma_f32 v[2:3], v[142:143], v[10:11], v[2:3] neg_lo:[0,0,1] neg_hi:[0,0,1]
	s_nop 0
	v_pk_add_f32 v[12:13], v[12:13], v[2:3]
	v_pk_mul_f32 v[2:3], v[130:131], v[10:11]
	s_nop 0
	v_pk_fma_f32 v[2:3], v[142:143], v[26:27], v[2:3]
	s_nop 0
	v_pk_add_f32 v[28:29], v[28:29], v[2:3]
	s_nop 0
	v_pk_mul_f32 v[2:3], v[130:131], v[28:29]
	s_nop 0
	v_pk_fma_f32 v[2:3], v[142:143], v[12:13], v[2:3] neg_lo:[0,0,1] neg_hi:[0,0,1]
	s_nop 0
	v_pk_add_f32 v[14:15], v[14:15], v[2:3]
	v_pk_mul_f32 v[2:3], v[130:131], v[12:13]
	ds_bpermute_b32 v127, v167, v14
	v_pk_fma_f32 v[2:3], v[142:143], v[28:29], v[2:3]
	ds_bpermute_b32 v155, v167, v15
	v_pk_add_f32 v[30:31], v[30:31], v[2:3]
	ds_bpermute_b32 v151, v167, v30
	ds_bpermute_b32 v182, v167, v31
	s_waitcnt lgkmcnt(3)
; #define LAS __attribute__((address_space(3)))
; __device__ __forceinline__ unsigned pk2(float lo, float hi) { f32x2 v = {lo, hi}; hbf2 r = __builtin_convertvector(v, hbf2); return __builtin_bit_cast(unsigned, r); }
; __device__ __forceinline__ cpx cfma(cpx a, cpx b, cpx c) { return {fmaf(a.r, b.r, fmaf(-a.i, b.i, c.r)), fmaf(a.r, b.i, fmaf(a.i, b.r, c.i))}; }
; template <bool FULL> __device__ __forceinline__ void scan32p(f32x16& xr, f32x16& xi, const cpx a1, const cpx a8, cpx& S, int hi) {
;     ...
;     const cpx mP = {Lr[7].x, Li[7].x}, mQ = {Lr[7].y, Li[7].y};
;     const cpx oP = {__shfl_xor(mP.r, 32), __shfl_xor(mP.i, 32)}, oQ = {__shfl_xor(mQ.r, 32), __shfl_xor(mQ.i, 32)};
;     const cpx e0P = hi == 0 ? mP : oP, e0Q = hi == 0 ? mQ : oQ, e1P = hi == 0 ? oP : mP, e1Q = hi == 0 ? oQ : mQ;
;     cpx c = S; const cpx cP0 = c; c = cfma(a8, c, e0P); const cpx cQ0 = c; c = cfma(a8, c, e0Q); const cpx cP1 = c; c = cfma(a8, c, e1P); const cpx cQ1 = c; c = cfma(a8, c, e1Q);
;     S = c;
;     if (FULL) {
;         const cpx myP = hi == 0 ? cP0 : cP1, myQ = hi == 0 ? cQ0 : cQ1;
;         f32x2 dr = {myP.r, myQ.r}, di = {myP.i, myQ.i};
; #pragma unroll
;         for (int q = 0; q < 8; ++q) {
;             const f32x2 tr = ar * dr - ai * di, ti = ar * di + ai * dr; dr = tr; di = ti;
;             const f32x2 sr = Lr[q] + dr, si = Li[q] + di;
;             xr[2 * q] = sr.x; xr[2 * q + 1] = sr.y; xi[2 * q] = si.x; xi[2 * q + 1] = si.y;
;         }
;     }
; }
; template <int PASS> __device__ __forceinline__ void ssm_unit(int unit, int lane, LAS unsigned char* wl, const bf16* X2, const float* slots, float* RSTD, const float* gmix, const float* AB, const float* A128, const bf16* BB, const bf16* CC, ...
;     ...
;         if (PASS == 2) {
; #pragma unroll
;             for (int b = 0; b < 4; ++b)
; #pragma unroll
;                 for (int e = 0; e < 2; ++e)
; #pragma unroll
;                     for (int q0 = 0; q0 < 8; q0 += 4) {
;                         u32x2 w; w.x = pk2(X[b][2 * q0 + e], X[b][2 * q0 + 2 + e]); w.y = pk2(X[b][2 * q0 + 4 + e], X[b][2 * q0 + 6 + e]);
;                         *(LAS u32x2*)(Sl + (b * 32 + n) * SSM_IROW + (16 * hi + 8 * e + q0) * 2) = w;
;                     }
	v_cndmask_b32_e64 v3, v127, v14, s[6:7]
	s_waitcnt lgkmcnt(2)
	v_cndmask_b32_e64 v183, v15, v155, s[6:7]
	s_waitcnt lgkmcnt(1)
	v_cndmask_b32_e64 v2, v151, v30, s[6:7]
	v_pk_fma_f32 v[2:3], v[136:137], v[132:133], v[2:3] op_sel:[0,1,0] op_sel_hi:[1,0,1]
	s_nop 0
	v_pk_fma_f32 v[164:165], v[146:147], v[132:133], v[2:3]
	v_cndmask_b32_e64 v3, v155, v15, s[6:7]
	s_waitcnt lgkmcnt(0)
	v_cndmask_b32_e64 v2, v182, v31, s[6:7]
	v_pk_fma_f32 v[2:3], v[136:137], v[164:165], v[2:3] op_sel:[0,1,0] op_sel_hi:[1,0,1]
	v_cndmask_b32_e64 v182, v31, v182, s[6:7]
	v_pk_fma_f32 v[180:181], v[146:147], v[164:165], v[2:3]
	v_cndmask_b32_e64 v3, v14, v127, s[6:7]
	v_cndmask_b32_e64 v2, v30, v151, s[6:7]
	v_pk_fma_f32 v[2:3], v[136:137], v[180:181], v[2:3] op_sel:[0,1,0] op_sel_hi:[1,0,1]
	v_cndmask_b32_e64 v184, v181, v133, s[6:7]
	v_pk_fma_f32 v[2:3], v[146:147], v[180:181], v[2:3]
	v_cndmask_b32_e64 v132, v180, v132, s[6:7]
	v_cndmask_b32_e64 v133, v2, v164, s[6:7]
	v_cndmask_b32_e64 v185, v3, v165, s[6:7]
	v_pk_mul_f32 v[164:165], v[130:131], v[132:133]
	v_pk_mul_f32 v[132:133], v[142:143], v[132:133]
	v_pk_fma_f32 v[164:165], v[142:143], v[184:185], v[164:165] neg_lo:[0,0,1] neg_hi:[0,0,1]
	v_pk_fma_f32 v[132:133], v[130:131], v[184:185], v[132:133]
	v_pk_add_f32 v[0:1], v[0:1], v[164:165]
	v_pk_mul_f32 v[180:181], v[130:131], v[132:133]
	v_pk_add_f32 v[16:17], v[16:17], v[132:133]
	v_pk_fma_f32 v[180:181], v[142:143], v[164:165], v[180:181] neg_lo:[0,0,1] neg_hi:[0,0,1]
	v_pk_mul_f32 v[164:165], v[130:131], v[164:165]
	v_ashrrev_i32_e32 v151, 31, v150
	v_pk_fma_f32 v[132:133], v[142:143], v[132:133], v[164:165]
	v_pk_add_f32 v[164:165], v[178:179], v[180:181]
	v_pk_mul_f32 v[178:179], v[130:131], v[132:133]
	v_pk_add_f32 v[18:19], v[18:19], v[132:133]
	v_pk_fma_f32 v[178:179], v[142:143], v[180:181], v[178:179] neg_lo:[0,0,1] neg_hi:[0,0,1]
	v_pk_mul_f32 v[180:181], v[130:131], v[180:181]
	v_pk_add_f32 v[4:5], v[4:5], v[178:179]
	v_pk_fma_f32 v[132:133], v[142:143], v[132:133], v[180:181]
	s_nop 0
	v_pk_mul_f32 v[180:181], v[130:131], v[132:133]
	v_pk_add_f32 v[20:21], v[20:21], v[132:133]
	v_pk_fma_f32 v[180:181], v[142:143], v[178:179], v[180:181] neg_lo:[0,0,1] neg_hi:[0,0,1]
	v_pk_mul_f32 v[178:179], v[130:131], v[178:179]
	v_pk_add_f32 v[6:7], v[6:7], v[180:181]
	v_pk_fma_f32 v[132:133], v[142:143], v[132:133], v[178:179]
	s_nop 0
	v_pk_mul_f32 v[178:179], v[130:131], v[132:133]
	v_pk_add_f32 v[22:23], v[22:23], v[132:133]
	v_pk_fma_f32 v[178:179], v[142:143], v[180:181], v[178:179] neg_lo:[0,0,1] neg_hi:[0,0,1]
	v_pk_mul_f32 v[180:181], v[130:131], v[180:181]
	v_pk_add_f32 v[8:9], v[8:9], v[178:179]
	v_pk_fma_f32 v[132:133], v[142:143], v[132:133], v[180:181]
	s_nop 0
	v_pk_mul_f32 v[180:181], v[130:131], v[132:133]
	v_pk_add_f32 v[24:25], v[24:25], v[132:133]
	v_pk_fma_f32 v[180:181], v[142:143], v[178:179], v[180:181] neg_lo:[0,0,1] neg_hi:[0,0,1]
	v_pk_mul_f32 v[178:179], v[130:131], v[178:179]
	v_pk_add_f32 v[10:11], v[10:11], v[180:181]
	v_pk_fma_f32 v[132:133], v[142:143], v[132:133], v[178:179]
	s_nop 0
	v_pk_mul_f32 v[178:179], v[130:131], v[132:133]
	v_pk_add_f32 v[26:27], v[26:27], v[132:133]
	v_pk_fma_f32 v[178:179], v[142:143], v[180:181], v[178:179] neg_lo:[0,0,1] neg_hi:[0,0,1]
	v_pk_mul_f32 v[180:181], v[130:131], v[180:181]
	v_pk_add_f32 v[12:13], v[12:13], v[178:179]
	v_pk_fma_f32 v[132:133], v[142:143], v[132:133], v[180:181]
	s_nop 0
	v_pk_mul_f32 v[180:181], v[130:131], v[132:133]
	v_pk_add_f32 v[28:29], v[28:29], v[132:133]
	v_pk_fma_f32 v[180:181], v[142:143], v[178:179], v[180:181] neg_lo:[0,0,1] neg_hi:[0,0,1]
	v_pk_mul_f32 v[178:179], v[130:131], v[178:179]
	v_pk_add_f32 v[14:15], v[14:15], v[180:181]
	v_pk_fma_f32 v[132:133], v[142:143], v[132:133], v[178:179]
	v_cvt_pk_bf16_f32 v178, v40, v42
	v_pk_add_f32 v[30:31], v[30:31], v[132:133]
	v_cvt_pk_bf16_f32 v132, v32, v174
	v_cvt_pk_bf16_f32 v133, v176, v38
	v_cvt_pk_bf16_f32 v32, v33, v175
	v_cvt_pk_bf16_f32 v33, v177, v39
	v_cvt_pk_bf16_f32 v38, v41, v43
	v_cvt_pk_bf16_f32 v39, v45, v47
	v_cvt_pk_bf16_f32 v179, v44, v46
	ds_write2_b64 v169, v[32:33], v[38:39] offset0:2 offset1:3
	v_cvt_pk_bf16_f32 v32, v0, v164
	v_cvt_pk_bf16_f32 v33, v4, v6
	v_cvt_pk_bf16_f32 v0, v1, v165
	v_cvt_pk_bf16_f32 v1, v5, v7
	v_cvt_pk_bf16_f32 v4, v9, v11
	v_cvt_pk_bf16_f32 v5, v13, v15
	ds_write2_b64 v169, v[132:133], v[178:179] offset1:1
	v_cvt_pk_bf16_f32 v38, v8, v10
	v_cvt_pk_bf16_f32 v39, v12, v14
	ds_write2_b64 v170, v[0:1], v[4:5] offset0:2 offset1:3
	v_cvt_pk_bf16_f32 v0, v48, v50
	v_cvt_pk_bf16_f32 v1, v52, v54
	v_add_u32_e32 v6, 0x1200, v169
	v_cvt_pk_bf16_f32 v4, v56, v58
	v_cvt_pk_bf16_f32 v5, v60, v62
	ds_write2_b64 v170, v[32:33], v[38:39] offset1:1
	ds_write2_b64 v6, v[0:1], v[4:5] offset1:1
	v_cvt_pk_bf16_f32 v0, v49, v51
	v_cvt_pk_bf16_f32 v1, v53, v55
	v_add_u32_e32 v6, 0x1210, v169
	v_cvt_pk_bf16_f32 v4, v57, v59
	v_cvt_pk_bf16_f32 v5, v61, v63
	ds_write2_b64 v6, v[0:1], v[4:5] offset1:1
	v_cvt_pk_bf16_f32 v0, v16, v18
	v_cvt_pk_bf16_f32 v1, v20, v22
	v_cvt_pk_bf16_f32 v4, v24, v26
	v_cvt_pk_bf16_f32 v5, v28, v30
	ds_write2_b64 v171, v[0:1], v[4:5] offset1:1
	v_cvt_pk_bf16_f32 v0, v17, v19
	v_cvt_pk_bf16_f32 v1, v21, v23
	v_cvt_pk_bf16_f32 v4, v25, v27
	v_cvt_pk_bf16_f32 v5, v29, v31
	ds_write2_b64 v171, v[0:1], v[4:5] offset0:2 offset1:3
	s_waitcnt lgkmcnt(0)
; #define LAS __attribute__((address_space(3)))
; #define LDS_WAIT() asm volatile("s_waitcnt lgkmcnt(0)" ::: "memory")
; __device__ __forceinline__ unsigned pk2(float lo, float hi) { f32x2 v = {lo, hi}; hbf2 r = __builtin_convertvector(v, hbf2); return __builtin_bit_cast(unsigned, r); }
; #define MFMA16(a, b, c) __builtin_amdgcn_mfma_f32_16x16x32_bf16((a), (b), (c), 0, 0, 0)
; #define SSM_LOAD(t) do { const int row_ = row0 + (t) * 32 + tok; nxw = *(const u32x4*)(X2 + (size_t)row_ * D + g * 16 + 8 * hi); \
;         if (PASS == 2) nrs = RSTD[row_]; else { const float* sl_ = slots + (size_t)row_ * 32; ns0 = *(const f32x4*)sl_; ns1 = *(const f32x4*)(sl_ + 4); ns2 = *(const f32x4*)(sl_ + 8); ns3 = *(const f32x4*)(sl_ + 12); } } while (0)
; template <int PASS> __device__ __forceinline__ void ssm_unit(int unit, int lane, LAS unsigned char* wl, const bf16* X2, const float* slots, float* RSTD, const float* gmix, const float* AB, const float* A128, const bf16* BB, const bf16* CC, ...
;     ...
;         if (t + 1 < ntile) SSM_LOAD(t + 1);
;     ...
;             LDS_WAIT();
; #pragma unroll
;             for (int th = 0; th < 2; ++th) {
;                 f32x4 y = {0.f, 0.f, 0.f, 0.f};
; #pragma unroll
;                 for (int ks = 0; ks < 4; ++ks) {
;                     const LAS unsigned char* tp = Sl + (32 * ks + 8 * kq + (c16 >> 2)) * SSM_IROW + th * 32 + 8 * (c16 & 3);
;                     const s16x4 lo = __builtin_amdgcn_ds_read_tr16_b64_v4i16((LAS s16x4*)tp), hi4 = __builtin_amdgcn_ds_read_tr16_b64_v4i16((LAS s16x4*)(tp + 4 * SSM_IROW));
;                     const bf16x8 sf = __builtin_shufflevector(lo, hi4, 0, 1, 2, 3, 4, 5, 6, 7); y = MFMA16(ccf[ks], sf, y); }
;                 const f32x4 uu = *(const LAS f32x4*)(Ul + (th * 16 + c16) * 16 + 4 * kq);
;                 y = y + dv * uu;
;                 u32x2 w; w.x = pk2(gelu_t(y[0]), gelu_t(y[1])); w.y = pk2(gelu_t(y[2]), gelu_t(y[3]));
;                 *(u32x2*)(YG + (size_t)(row0 + t * 32 + th * 16 + c16) * D + g * 16 + 4 * kq) = w;
;             }
;             LDS_WAIT();
;         }
	ds_read_b64_tr_b16 v[4:5], v172
	ds_read_b64_tr_b16 v[6:7], v172 offset:288
	ds_read_b64_tr_b16 v[8:9], v172 offset:2304
	ds_read_b64_tr_b16 v[10:11], v172 offset:2592
	ds_read_b64_tr_b16 v[14:15], v172 offset:320
	ds_read_b64_tr_b16 v[12:13], v172 offset:32
	s_waitcnt lgkmcnt(4)
	v_mfma_f32_16x16x32_bf16 v[4:7], v[80:83], v[4:7], 0
	ds_read_b64_tr_b16 v[18:19], v172 offset:2624
	ds_read_b64_tr_b16 v[16:17], v172 offset:2336
	v_pk_fma_f32 v[0:1], v[136:137], v[2:3], v[182:183] op_sel:[0,1,0] op_sel_hi:[1,0,1]
	v_pk_fma_f32 v[164:165], v[148:149], v[34:35], v[36:37]
	s_waitcnt lgkmcnt(4)
	v_mfma_f32_16x16x32_bf16 v[4:7], v[84:87], v[8:11], v[4:7]
	ds_read_b64_tr_b16 v[8:9], v172 offset:4608
	ds_read_b64_tr_b16 v[10:11], v172 offset:4896
	ds_read_b64_tr_b16 v[20:21], v172 offset:6912
	ds_read_b64_tr_b16 v[22:23], v172 offset:7200
	ds_read_b64_tr_b16 v[26:27], v172 offset:4928
	ds_read_b64_tr_b16 v[24:25], v172 offset:4640
	v_pk_fma_f32 v[132:133], v[146:147], v[2:3], v[0:1]
	s_waitcnt lgkmcnt(4)
	v_mfma_f32_16x16x32_bf16 v[4:7], v[88:91], v[8:11], v[4:7]
	ds_read_b128 v[8:11], v173 offset:9216
	ds_read_b64_tr_b16 v[30:31], v172 offset:7232
	ds_read_b64_tr_b16 v[28:29], v172 offset:6944
	s_waitcnt lgkmcnt(5)
	v_mfma_f32_16x16x32_bf16 v[4:7], v[92:95], v[20:23], v[4:7]
	ds_read_b128 v[20:23], v173 offset:10240
	s_waitcnt lgkmcnt(3)
	s_nop 5
	v_pk_fma_f32 v[8:9], v[96:97], v[8:9], v[4:5]
	v_pk_fma_f32 v[10:11], v[98:99], v[10:11], v[6:7]
	v_mul_f32_e32 v4, 0x3d922279, v8
	v_fmaak_f32 v4, v8, v4, 0x3fcc422a
	v_mul_f32_e32 v5, 0x3d922279, v9
	v_mul_f32_e64 v4, v8, -v4
	v_fmaak_f32 v5, v9, v5, 0x3fcc422a
	v_mul_f32_e32 v4, 0x3fb8aa3b, v4
	v_mul_f32_e64 v5, v9, -v5
	v_exp_f32_e32 v4, v4
	v_mul_f32_e32 v5, 0x3fb8aa3b, v5
	v_exp_f32_e32 v5, v5
	v_add_f32_e32 v4, 1.0, v4
	v_rcp_f32_e32 v32, v4
	v_add_f32_e32 v4, 1.0, v5
	v_rcp_f32_e32 v33, v4
	v_mul_f32_e32 v4, 0x3d922279, v10
	v_fmaak_f32 v4, v10, v4, 0x3fcc422a
	v_mul_f32_e64 v4, v10, -v4
	v_mul_f32_e32 v4, 0x3fb8aa3b, v4
	v_exp_f32_e32 v4, v4
	v_mul_f32_e32 v5, 0x3d922279, v11
	v_fmaak_f32 v5, v11, v5, 0x3fcc422a
	v_mul_f32_e64 v5, v11, -v5
	v_mul_f32_e32 v5, 0x3fb8aa3b, v5
	v_add_f32_e32 v4, 1.0, v4
	v_exp_f32_e32 v39, v5
	v_rcp_f32_e32 v38, v4
	v_mfma_f32_16x16x32_bf16 v[4:7], v[80:83], v[12:15], 0
	v_mul_f32_e64 v8, v8, v32
	v_mul_f32_e64 v9, v9, v33
	v_add_f32_e32 v12, 1.0, v39
	v_rcp_f32_e32 v39, v12
	v_mfma_f32_16x16x32_bf16 v[4:7], v[84:87], v[16:19], v[4:7]
	v_cvt_pk_bf16_f32 v8, v8, v9
	v_pk_mul_f32 v[10:11], v[10:11], v[38:39]
	v_mfma_f32_16x16x32_bf16 v[4:7], v[88:91], v[24:27], v[4:7]
	v_cvt_pk_bf16_f32 v9, v10, v11
	v_lshlrev_b64 v[10:11], 11, v[150:151]
	v_lshl_add_u64 v[10:11], v[144:145], 0, v[10:11]
	s_waitcnt lgkmcnt(1)
	v_mfma_f32_16x16x32_bf16 v[4:7], v[92:95], v[28:31], v[4:7]
	global_store_dwordx2 v[10:11], v[8:9], off
	s_waitcnt lgkmcnt(0)
	s_nop 5
	v_pk_fma_f32 v[4:5], v[96:97], v[20:21], v[4:5]
	v_pk_fma_f32 v[6:7], v[98:99], v[22:23], v[6:7]
	v_mul_f32_e32 v12, 0x3d922279, v4
	v_mul_f32_e32 v13, 0x3d922279, v5
	v_mul_f32_e32 v14, 0x3d922279, v6
	v_mul_f32_e32 v15, 0x3d922279, v7
	v_fmaak_f32 v12, v4, v12, 0x3fcc422a
	v_fmaak_f32 v13, v5, v13, 0x3fcc422a
	v_fmaak_f32 v14, v6, v14, 0x3fcc422a
	v_fmaak_f32 v15, v7, v15, 0x3fcc422a
	v_mul_f32_e64 v12, v4, -v12
	v_mul_f32_e64 v13, v5, -v13
	v_mul_f32_e64 v14, v6, -v14
	v_mul_f32_e64 v15, v7, -v15
	v_mul_f32_e32 v12, 0x3fb8aa3b, v12
	v_mul_f32_e32 v13, 0x3fb8aa3b, v13
	v_mul_f32_e32 v14, 0x3fb8aa3b, v14
	v_mul_f32_e32 v15, 0x3fb8aa3b, v15
	v_exp_f32_e32 v12, v12
	v_exp_f32_e32 v13, v13
	v_exp_f32_e32 v14, v14
	v_exp_f32_e32 v15, v15
	v_add_f32_e32 v12, 1.0, v12
	v_add_f32_e32 v13, 1.0, v13
	v_add_f32_e32 v14, 1.0, v14
	v_add_f32_e32 v15, 1.0, v15
	v_rcp_f32_e32 v12, v12
	v_rcp_f32_e32 v13, v13
	v_rcp_f32_e32 v14, v14
	v_rcp_f32_e32 v15, v15
	v_pk_mul_f32 v[4:5], v[4:5], v[12:13]
	s_nop 0
	v_cvt_pk_bf16_f32 v4, v4, v5
	v_pk_mul_f32 v[6:7], v[6:7], v[14:15]
	s_nop 0
	v_cvt_pk_bf16_f32 v5, v6, v7
	v_add_u32_e32 v6, 16, v150
	v_ashrrev_i32_e32 v7, 31, v6
	v_lshlrev_b64 v[6:7], 11, v[6:7]
	v_lshl_add_u64 v[6:7], v[144:145], 0, v[6:7]
	global_store_dwordx2 v[6:7], v[4:5], off
	s_waitcnt lgkmcnt(0)
	v_add_u32_e32 v150, 32, v150
	s_waitcnt vmcnt(2)
	v_mov_b64_e32 v[0:1], v[108:109]
	v_mov_b64_e32 v[2:3], v[110:111]
	v_mov_b32_e32 v4, v112
	s_cbranch_scc1 .LBB0_737
	s_branch .Lp7_tile_next
.LBB0_735:
	s_waitcnt vmcnt(0)
	v_mov_b32_e32 v4, v206
.Lp7_tile_next:
	s_add_i32 s46, s46, 1
	s_cmp_ge_u32 s46, s68
	v_mov_b32_e32 v112, v4
	s_cbranch_scc1 .LBB0_734
	v_ashrrev_i32_e32 v155, 31, v154
	v_lshlrev_b64 v[8:9], 11, v[154:155]
	v_lshl_add_u64 v[8:9], v[138:139], 0, v[8:9]
	v_lshl_add_u64 v[6:7], v[154:155], 2, s[22:23]
	global_load_dwordx4 v[108:111], v[8:9], off
	global_load_dword v112, v[6:7], off
	s_branch .LBB0_734

; __global__ void __launch_bounds__(512, 2) mk_fwd(Params p) {
	.amdhsa_kernel _Z6mk_fwd6Params
		.amdhsa_group_segment_fixed_size 0
		.amdhsa_private_segment_fixed_size 0
		.amdhsa_kernarg_size 472
		.amdhsa_user_sgpr_count 2
		.amdhsa_user_sgpr_dispatch_ptr 0
		.amdhsa_user_sgpr_queue_ptr 0
		.amdhsa_user_sgpr_kernarg_segment_ptr 1
		.amdhsa_user_sgpr_dispatch_id 0
		.amdhsa_user_sgpr_kernarg_preload_length 0
		.amdhsa_user_sgpr_kernarg_preload_offset 0
		.amdhsa_user_sgpr_private_segment_size 0
		.amdhsa_uses_dynamic_stack 0
		.amdhsa_enable_private_segment 0
		.amdhsa_system_sgpr_workgroup_id_x 1
		.amdhsa_system_sgpr_workgroup_id_y 0
		.amdhsa_system_sgpr_workgroup_id_z 0
		.amdhsa_system_sgpr_workgroup_info 0
		.amdhsa_system_vgpr_workitem_id 2
		.amdhsa_next_free_vgpr 239
		.amdhsa_next_free_sgpr 102
		.amdhsa_accum_offset 240
		.amdhsa_reserve_vcc 1
		.amdhsa_float_round_mode_32 0
		.amdhsa_float_round_mode_16_64 0
		.amdhsa_float_denorm_mode_32 3
		.amdhsa_float_denorm_mode_16_64 3
		.amdhsa_dx10_clamp 1
		.amdhsa_ieee_mode 1
		.amdhsa_fp16_overflow 0
		.amdhsa_tg_split 0
		.amdhsa_exception_fp_ieee_invalid_op 0
		.amdhsa_exception_fp_denorm_src 0
		.amdhsa_exception_fp_ieee_div_zero 0
		.amdhsa_exception_fp_ieee_overflow 0
		.amdhsa_exception_fp_ieee_underflow 0
		.amdhsa_exception_fp_ieee_inexact 0
		.amdhsa_exception_int_div_zero 0
	.end_amdhsa_kernel

; __global__ void __launch_bounds__(512, 2) mk_fwd(Params p) {
.Lfunc_end0:
	.size	_Z6mk_fwd6Params, .Lfunc_end0-_Z6mk_fwd6Params
	.set _Z6mk_fwd6Params.num_vgpr, 239
	.set _Z6mk_fwd6Params.num_agpr, 0
	.set _Z6mk_fwd6Params.numbered_sgpr, 102
	.set _Z6mk_fwd6Params.num_named_barrier, 0
	.set _Z6mk_fwd6Params.private_seg_size, 0
	.set _Z6mk_fwd6Params.uses_vcc, 1
	.set _Z6mk_fwd6Params.uses_flat_scratch, 0
	.set _Z6mk_fwd6Params.has_dyn_sized_stack, 0
	.set _Z6mk_fwd6Params.has_recursion, 0
	.set _Z6mk_fwd6Params.has_indirect_call, 0

; __global__ void __launch_bounds__(512, 2) mk_fwd(Params p) {
amdhsa.kernels:
  - .agpr_count:     0
    .args:
      - .offset:         0
        .size:           216
        .value_kind:     by_value
      - .offset:         216
        .size:           4
        .value_kind:     hidden_block_count_x
      - .offset:         220
        .size:           4
        .value_kind:     hidden_block_count_y
      - .offset:         224
        .size:           4
        .value_kind:     hidden_block_count_z
      - .offset:         228
        .size:           2
        .value_kind:     hidden_group_size_x
      - .offset:         230
        .size:           2
        .value_kind:     hidden_group_size_y
      - .offset:         232
        .size:           2
        .value_kind:     hidden_group_size_z
      - .offset:         234
        .size:           2
        .value_kind:     hidden_remainder_x
      - .offset:         236
        .size:           2
        .value_kind:     hidden_remainder_y
      - .offset:         238
        .size:           2
        .value_kind:     hidden_remainder_z
      - .offset:         256
        .size:           8
        .value_kind:     hidden_global_offset_x
      - .offset:         264
        .size:           8
        .value_kind:     hidden_global_offset_y
      - .offset:         272
        .size:           8
        .value_kind:     hidden_global_offset_z
      - .offset:         280
        .size:           2
        .value_kind:     hidden_grid_dims
      - .offset:         304
        .size:           8
        .value_kind:     hidden_multigrid_sync_arg
      - .offset:         336
        .size:           4
        .value_kind:     hidden_dynamic_lds_size
    .group_segment_fixed_size: 0
    .kernarg_segment_align: 8
    .kernarg_segment_size: 472
    .language:       OpenCL C
    .language_version:
      - 2
      - 0
    .max_flat_workgroup_size: 512
    .name:           _Z6mk_fwd6Params
    .private_segment_fixed_size: 0
    .sgpr_count:     108
    .sgpr_spill_count: 4
    .symbol:         _Z6mk_fwd6Params.kd
    .uniform_work_group_size: 1
    .uses_dynamic_stack: false
    .vgpr_count:     239
    .vgpr_spill_count: 0
    .wavefront_size: 64
